# scan consumer: 4 reg sets, loads 3 ahead, wait every 2 steps, y partials via ds_write2st64, barrier at step 14, no tail
# baseline (speedup 1.0000x reference)
; #define LAS __attribute__((address_space(3)))
; DI void rwkv_scan_phase(int wv, const Params& P, LAS unsigned char* lds) {
;     ...
;             const int cg = lane & 15, rloc = wave * 4 + (lane >> 4);
;             f32x4 S = (f32x4){0.f, 0.f, 0.f, 0.f};
;             __syncthreads();
;             __builtin_amdgcn_s_setprio(3);
; #pragma unroll 1
;             for (int ck = 0; ck < nck; ++ck) { const int buf = ck & 1;
;                 const LAS float* sb = stg + buf * RW_T * 5 * 64 + 4 * cg; const LAS float* vb = vst + buf * RW_T * 8 + rloc; LAS float* yb = ybuf + buf * RW_T * 128 + wave * 64 + lane;
;                 const unsigned sba = (unsigned)(size_t)sb, vba = (unsigned)(size_t)vb;
;                 f32x4 nkA, ddA, bbA, kpA, rrA, nkB, ddB, bbB, kpB, rrB; float vvA, vvB;
;     ...
;                 f32x2 yacc = (f32x2){0.f, 0.f};
;                 unsigned sbt = sba, vbt = vba; LAS float* ybt = yb;
;                 RW_LDS_LOAD(A, 0); RW_LDS_WAIT(A);
; #pragma unroll 1
;                 for (int tt = 0; tt < RW_T; tt += 16) { sbt = sba + (unsigned)tt * 1280u; vbt = vba + (unsigned)tt * 32u; ybt = yb + tt * 128;
;                     RW_LDS_LOAD(B, 1); RW_STEP(A, 0); RW_LDS_WAIT(B);
;                     RW_LDS_LOAD(A, 2); RW_STEP(B, 1); RW_LDS_WAIT(A);
;                     RW_LDS_LOAD(B, 3); RW_STEP(A, 2); RW_LDS_WAIT(B);
;                     RW_LDS_LOAD(A, 4); RW_STEP(B, 3); RW_LDS_WAIT(A);
;                     RW_LDS_LOAD(B, 5); RW_STEP(A, 4); RW_LDS_WAIT(B);
;                     RW_LDS_LOAD(A, 6); RW_STEP(B, 5); RW_LDS_WAIT(A);
;                     RW_LDS_LOAD(B, 7); RW_STEP(A, 6); RW_LDS_WAIT(B);
;                     RW_LDS_LOAD(A, 8); RW_STEP(B, 7); RW_LDS_WAIT(A);
;                     RW_LDS_LOAD(B, 9); RW_STEP(A, 8); RW_LDS_WAIT(B);
;                     RW_LDS_LOAD(A, 10); RW_STEP(B, 9); RW_LDS_WAIT(A);
;                     RW_LDS_LOAD(B, 11); RW_STEP(A, 10); RW_LDS_WAIT(B);
;                     RW_LDS_LOAD(A, 12); RW_STEP(B, 11); RW_LDS_WAIT(A);
;                     RW_LDS_LOAD(B, 13); RW_STEP(A, 12); RW_LDS_WAIT(B);
;                     RW_LDS_LOAD(A, 14); RW_STEP(B, 13); RW_LDS_WAIT(A);
;                     RW_LDS_LOAD(B, 15); RW_STEP(A, 14); RW_LDS_WAIT(B);
;                     RW_LDS_LOAD(A, 16); RW_STEP(B, 15); RW_LDS_WAIT(A);
;                 }
.LBB0_3177:
	s_waitcnt lgkmcnt(0)
	s_barrier
	s_and_saveexec_b64 s[20:21], s[2:3]
	s_xor_b64 s[20:21], exec, s[20:21]
	s_cbranch_execz .LBB0_3185
	s_barrier
	s_setprio 3
	v_add_u32_e32 v42, 0xfffec000, v63
	v_mov_b32_e32 v58, 0
	v_mov_b32_e32 v59, 0
	v_lshl_add_u32 v42, v42, 6, v45
	v_mov_b32_e32 v60, 0
	v_mov_b32_e32 v61, 0
	v_add_u32_e32 v42, 0x400, v42
	v_add_u32_e32 v62, 0x3800, v66
	s_mov_b32 s47, 0
	s_mov_b32 s42, 0
	v_mov_b32_e32 v74, v45
	v_mov_b32_e32 v75, v42
	v_add_u32_e32 v67, s42, v62
	v_add_u32_e32 v72, 0x4000, v62
	ds_read_b128 v[0:3], v74
	ds_read_b128 v[16:19], v74 offset:256
	ds_read_b128 v[4:7], v74 offset:512
	ds_read_b128 v[12:15], v75
	ds_read_b128 v[8:11], v74 offset:768
	ds_read_b128 v[20:23], v74 offset:3072
	ds_read_b128 v[36:39], v74 offset:3328
	ds_read_b128 v[24:27], v74 offset:3584
	ds_read_b128 v[32:35], v75 offset:3072
	ds_read_b128 v[28:31], v74 offset:3840
	ds_read_b128 v[46:49], v74 offset:6144
	ds_read_b128 v[76:79], v74 offset:6400
	ds_read_b128 v[50:53], v74 offset:6656
	ds_read_b128 v[68:71], v75 offset:6144
	ds_read_b128 v[54:57], v74 offset:6912
.Lscan_chunk:
	s_waitcnt lgkmcnt(5)
	v_pk_mul_f32 v[0:1], v[58:59], v[0:1] op_sel_hi:[0,1]
	v_pk_fma_f32 v[0:1], v[58:59], v[2:3], v[0:1] op_sel:[1,0,0] op_sel_hi:[1,1,1]
	v_pk_fma_f32 v[0:1], v[60:61], v[16:17], v[0:1] op_sel_hi:[0,1,1]
	v_pk_fma_f32 v[0:1], v[60:61], v[18:19], v[0:1] op_sel:[1,0,0] op_sel_hi:[1,1,1]
	ds_write2st64_b32 v72, v81, v1 offset0:28 offset1:30
	v_mov_b32_e32 v72, v67
	v_add_f32_dpp v0, v0, v0 quad_perm:[1,0,3,2] row_mask:0xf bank_mask:0xf bound_ctrl:1
	v_pk_fma_f32 v[12:13], v[58:59], v[4:5], v[12:13]
	ds_read_b128 v[80:83], v74 offset:9216
	v_add_f32_dpp v0, v0, v0 quad_perm:[2,3,0,1] row_mask:0xf bank_mask:0xf bound_ctrl:1
	ds_read_b128 v[96:99], v74 offset:9472
	ds_read_b128 v[84:87], v74 offset:9728
	v_add_f32_dpp v0, v0, v0 row_half_mirror row_mask:0xf bank_mask:0xf bound_ctrl:1
	ds_read_b128 v[92:95], v75 offset:9216
	ds_read_b128 v[88:91], v74 offset:9984
	v_add_f32_dpp v0, v0, v0 row_mirror row_mask:0xf bank_mask:0xf bound_ctrl:1
	v_pk_fma_f32 v[14:15], v[60:61], v[6:7], v[14:15]
	v_pk_fma_f32 v[58:59], v[8:9], v[0:1], v[12:13] op_sel_hi:[1,0,1]
	v_pk_fma_f32 v[60:61], v[10:11], v[0:1], v[14:15] op_sel_hi:[1,0,1]
	ds_read_b128 v[0:3], v74 offset:12288
	v_pk_mul_f32 v[20:21], v[58:59], v[20:21] op_sel_hi:[0,1]
	v_pk_fma_f32 v[20:21], v[58:59], v[22:23], v[20:21] op_sel:[1,0,0] op_sel_hi:[1,1,1]
	v_pk_fma_f32 v[20:21], v[60:61], v[36:37], v[20:21] op_sel_hi:[0,1,1]
	v_pk_fma_f32 v[20:21], v[60:61], v[38:39], v[20:21] op_sel:[1,0,0] op_sel_hi:[1,1,1]
	v_pk_fma_f32 v[32:33], v[58:59], v[24:25], v[32:33]
	v_pk_fma_f32 v[34:35], v[60:61], v[26:27], v[34:35]
	v_add_f32_dpp v20, v20, v20 quad_perm:[1,0,3,2] row_mask:0xf bank_mask:0xf bound_ctrl:1
	ds_read_b128 v[16:19], v74 offset:12544
	ds_read_b128 v[4:7], v74 offset:12800
	v_add_f32_dpp v20, v20, v20 quad_perm:[2,3,0,1] row_mask:0xf bank_mask:0xf bound_ctrl:1
	ds_read_b128 v[12:15], v75 offset:12288
	ds_read_b128 v[8:11], v74 offset:13056
	v_add_f32_dpp v20, v20, v20 row_half_mirror row_mask:0xf bank_mask:0xf bound_ctrl:1
	s_nop 1
	v_add_f32_dpp v20, v20, v20 row_mirror row_mask:0xf bank_mask:0xf bound_ctrl:1
	v_pk_fma_f32 v[58:59], v[28:29], v[20:21], v[32:33] op_sel_hi:[1,0,1]
	v_pk_fma_f32 v[60:61], v[30:31], v[20:21], v[34:35] op_sel_hi:[1,0,1]
	s_waitcnt lgkmcnt(5)
	v_pk_mul_f32 v[46:47], v[58:59], v[46:47] op_sel_hi:[0,1]
	v_pk_fma_f32 v[46:47], v[58:59], v[48:49], v[46:47] op_sel:[1,0,0] op_sel_hi:[1,1,1]
	v_pk_fma_f32 v[46:47], v[60:61], v[76:77], v[46:47] op_sel_hi:[0,1,1]
	v_pk_fma_f32 v[46:47], v[60:61], v[78:79], v[46:47] op_sel:[1,0,0] op_sel_hi:[1,1,1]
	ds_write2st64_b32 v72, v21, v47 offset0:0 offset1:2
	v_pk_fma_f32 v[68:69], v[58:59], v[50:51], v[68:69]
	v_add_f32_dpp v46, v46, v46 quad_perm:[1,0,3,2] row_mask:0xf bank_mask:0xf bound_ctrl:1
	ds_read_b128 v[20:23], v74 offset:15360
	ds_read_b128 v[36:39], v74 offset:15616
	v_add_f32_dpp v46, v46, v46 quad_perm:[2,3,0,1] row_mask:0xf bank_mask:0xf bound_ctrl:1
	ds_read_b128 v[24:27], v74 offset:15872
	ds_read_b128 v[32:35], v75 offset:15360
	v_add_f32_dpp v46, v46, v46 row_half_mirror row_mask:0xf bank_mask:0xf bound_ctrl:1
	ds_read_b128 v[28:31], v74 offset:16128
	v_pk_fma_f32 v[70:71], v[60:61], v[52:53], v[70:71]
	v_add_f32_dpp v46, v46, v46 row_mirror row_mask:0xf bank_mask:0xf bound_ctrl:1
	v_pk_fma_f32 v[58:59], v[54:55], v[46:47], v[68:69] op_sel_hi:[1,0,1]
	v_pk_fma_f32 v[60:61], v[56:57], v[46:47], v[70:71] op_sel_hi:[1,0,1]
	ds_read_b128 v[46:49], v74 offset:18432
	v_pk_mul_f32 v[80:81], v[58:59], v[80:81] op_sel_hi:[0,1]
	v_pk_fma_f32 v[80:81], v[58:59], v[82:83], v[80:81] op_sel:[1,0,0] op_sel_hi:[1,1,1]
	v_pk_fma_f32 v[80:81], v[60:61], v[96:97], v[80:81] op_sel_hi:[0,1,1]
	v_pk_fma_f32 v[80:81], v[60:61], v[98:99], v[80:81] op_sel:[1,0,0] op_sel_hi:[1,1,1]
	v_pk_fma_f32 v[92:93], v[58:59], v[84:85], v[92:93]
	v_pk_fma_f32 v[94:95], v[60:61], v[86:87], v[94:95]
	v_add_f32_dpp v80, v80, v80 quad_perm:[1,0,3,2] row_mask:0xf bank_mask:0xf bound_ctrl:1
	ds_read_b128 v[76:79], v74 offset:18688
	ds_read_b128 v[50:53], v74 offset:18944
	v_add_f32_dpp v80, v80, v80 quad_perm:[2,3,0,1] row_mask:0xf bank_mask:0xf bound_ctrl:1
	ds_read_b128 v[68:71], v75 offset:18432
	ds_read_b128 v[54:57], v74 offset:19200
	v_add_f32_dpp v80, v80, v80 row_half_mirror row_mask:0xf bank_mask:0xf bound_ctrl:1
	s_nop 1
	v_add_f32_dpp v80, v80, v80 row_mirror row_mask:0xf bank_mask:0xf bound_ctrl:1
	v_pk_fma_f32 v[58:59], v[88:89], v[80:81], v[92:93] op_sel_hi:[1,0,1]
	v_pk_fma_f32 v[60:61], v[90:91], v[80:81], v[94:95] op_sel_hi:[1,0,1]
	s_waitcnt lgkmcnt(5)
	v_pk_mul_f32 v[0:1], v[58:59], v[0:1] op_sel_hi:[0,1]
	v_pk_fma_f32 v[0:1], v[58:59], v[2:3], v[0:1] op_sel:[1,0,0] op_sel_hi:[1,1,1]
	v_pk_fma_f32 v[0:1], v[60:61], v[16:17], v[0:1] op_sel_hi:[0,1,1]
	v_pk_fma_f32 v[0:1], v[60:61], v[18:19], v[0:1] op_sel:[1,0,0] op_sel_hi:[1,1,1]
	ds_write2st64_b32 v72, v81, v1 offset0:4 offset1:6
	v_pk_fma_f32 v[12:13], v[58:59], v[4:5], v[12:13]
	v_add_f32_dpp v0, v0, v0 quad_perm:[1,0,3,2] row_mask:0xf bank_mask:0xf bound_ctrl:1
	ds_read_b128 v[80:83], v74 offset:21504
	ds_read_b128 v[96:99], v74 offset:21760
	v_add_f32_dpp v0, v0, v0 quad_perm:[2,3,0,1] row_mask:0xf bank_mask:0xf bound_ctrl:1
	ds_read_b128 v[84:87], v74 offset:22016
	ds_read_b128 v[92:95], v75 offset:21504
	v_add_f32_dpp v0, v0, v0 row_half_mirror row_mask:0xf bank_mask:0xf bound_ctrl:1
	ds_read_b128 v[88:91], v74 offset:22272
	v_pk_fma_f32 v[14:15], v[60:61], v[6:7], v[14:15]
	v_add_f32_dpp v0, v0, v0 row_mirror row_mask:0xf bank_mask:0xf bound_ctrl:1
	v_pk_fma_f32 v[58:59], v[8:9], v[0:1], v[12:13] op_sel_hi:[1,0,1]
	v_pk_fma_f32 v[60:61], v[10:11], v[0:1], v[14:15] op_sel_hi:[1,0,1]
	ds_read_b128 v[0:3], v74 offset:24576
	v_pk_mul_f32 v[20:21], v[58:59], v[20:21] op_sel_hi:[0,1]
	v_pk_fma_f32 v[20:21], v[58:59], v[22:23], v[20:21] op_sel:[1,0,0] op_sel_hi:[1,1,1]
	v_pk_fma_f32 v[20:21], v[60:61], v[36:37], v[20:21] op_sel_hi:[0,1,1]
	v_pk_fma_f32 v[20:21], v[60:61], v[38:39], v[20:21] op_sel:[1,0,0] op_sel_hi:[1,1,1]
	v_pk_fma_f32 v[32:33], v[58:59], v[24:25], v[32:33]
	v_pk_fma_f32 v[34:35], v[60:61], v[26:27], v[34:35]
	v_add_f32_dpp v20, v20, v20 quad_perm:[1,0,3,2] row_mask:0xf bank_mask:0xf bound_ctrl:1
	ds_read_b128 v[16:19], v74 offset:24832
	ds_read_b128 v[4:7], v74 offset:25088
	v_add_f32_dpp v20, v20, v20 quad_perm:[2,3,0,1] row_mask:0xf bank_mask:0xf bound_ctrl:1
	ds_read_b128 v[12:15], v75 offset:24576
	ds_read_b128 v[8:11], v74 offset:25344
	v_add_f32_dpp v20, v20, v20 row_half_mirror row_mask:0xf bank_mask:0xf bound_ctrl:1
	s_nop 1
	v_add_f32_dpp v20, v20, v20 row_mirror row_mask:0xf bank_mask:0xf bound_ctrl:1
	v_pk_fma_f32 v[58:59], v[28:29], v[20:21], v[32:33] op_sel_hi:[1,0,1]
	v_pk_fma_f32 v[60:61], v[30:31], v[20:21], v[34:35] op_sel_hi:[1,0,1]
	s_waitcnt lgkmcnt(5)
	v_pk_mul_f32 v[46:47], v[58:59], v[46:47] op_sel_hi:[0,1]
	v_pk_fma_f32 v[46:47], v[58:59], v[48:49], v[46:47] op_sel:[1,0,0] op_sel_hi:[1,1,1]
	v_pk_fma_f32 v[46:47], v[60:61], v[76:77], v[46:47] op_sel_hi:[0,1,1]
	v_pk_fma_f32 v[46:47], v[60:61], v[78:79], v[46:47] op_sel:[1,0,0] op_sel_hi:[1,1,1]
	ds_write2st64_b32 v72, v21, v47 offset0:8 offset1:10
	v_pk_fma_f32 v[68:69], v[58:59], v[50:51], v[68:69]
	v_add_f32_dpp v46, v46, v46 quad_perm:[1,0,3,2] row_mask:0xf bank_mask:0xf bound_ctrl:1
	ds_read_b128 v[20:23], v74 offset:27648
	ds_read_b128 v[36:39], v74 offset:27904
	v_add_f32_dpp v46, v46, v46 quad_perm:[2,3,0,1] row_mask:0xf bank_mask:0xf bound_ctrl:1
	ds_read_b128 v[24:27], v74 offset:28160
	ds_read_b128 v[32:35], v75 offset:27648
	v_add_f32_dpp v46, v46, v46 row_half_mirror row_mask:0xf bank_mask:0xf bound_ctrl:1
	ds_read_b128 v[28:31], v74 offset:28416
	v_pk_fma_f32 v[70:71], v[60:61], v[52:53], v[70:71]
	v_add_f32_dpp v46, v46, v46 row_mirror row_mask:0xf bank_mask:0xf bound_ctrl:1
	v_pk_fma_f32 v[58:59], v[54:55], v[46:47], v[68:69] op_sel_hi:[1,0,1]
	v_pk_fma_f32 v[60:61], v[56:57], v[46:47], v[70:71] op_sel_hi:[1,0,1]
	ds_read_b128 v[46:49], v74 offset:30720
	v_pk_mul_f32 v[80:81], v[58:59], v[80:81] op_sel_hi:[0,1]
	v_pk_fma_f32 v[80:81], v[58:59], v[82:83], v[80:81] op_sel:[1,0,0] op_sel_hi:[1,1,1]
	v_pk_fma_f32 v[80:81], v[60:61], v[96:97], v[80:81] op_sel_hi:[0,1,1]
	v_pk_fma_f32 v[80:81], v[60:61], v[98:99], v[80:81] op_sel:[1,0,0] op_sel_hi:[1,1,1]
	v_pk_fma_f32 v[92:93], v[58:59], v[84:85], v[92:93]
	v_pk_fma_f32 v[94:95], v[60:61], v[86:87], v[94:95]
	v_add_f32_dpp v80, v80, v80 quad_perm:[1,0,3,2] row_mask:0xf bank_mask:0xf bound_ctrl:1
	ds_read_b128 v[76:79], v74 offset:30976
	ds_read_b128 v[50:53], v74 offset:31232
	v_add_f32_dpp v80, v80, v80 quad_perm:[2,3,0,1] row_mask:0xf bank_mask:0xf bound_ctrl:1
	ds_read_b128 v[68:71], v75 offset:30720
	ds_read_b128 v[54:57], v74 offset:31488
	v_add_f32_dpp v80, v80, v80 row_half_mirror row_mask:0xf bank_mask:0xf bound_ctrl:1
	s_nop 1
	v_add_f32_dpp v80, v80, v80 row_mirror row_mask:0xf bank_mask:0xf bound_ctrl:1
	v_pk_fma_f32 v[58:59], v[88:89], v[80:81], v[92:93] op_sel_hi:[1,0,1]
	v_pk_fma_f32 v[60:61], v[90:91], v[80:81], v[94:95] op_sel_hi:[1,0,1]
	s_waitcnt lgkmcnt(5)
	v_pk_mul_f32 v[0:1], v[58:59], v[0:1] op_sel_hi:[0,1]
	v_pk_fma_f32 v[0:1], v[58:59], v[2:3], v[0:1] op_sel:[1,0,0] op_sel_hi:[1,1,1]
	v_pk_fma_f32 v[0:1], v[60:61], v[16:17], v[0:1] op_sel_hi:[0,1,1]
	v_pk_fma_f32 v[0:1], v[60:61], v[18:19], v[0:1] op_sel:[1,0,0] op_sel_hi:[1,1,1]
	ds_write2st64_b32 v72, v81, v1 offset0:12 offset1:14
	v_pk_fma_f32 v[12:13], v[58:59], v[4:5], v[12:13]
	v_add_f32_dpp v0, v0, v0 quad_perm:[1,0,3,2] row_mask:0xf bank_mask:0xf bound_ctrl:1
	ds_read_b128 v[80:83], v74 offset:33792
	ds_read_b128 v[96:99], v74 offset:34048
	v_add_f32_dpp v0, v0, v0 quad_perm:[2,3,0,1] row_mask:0xf bank_mask:0xf bound_ctrl:1
	ds_read_b128 v[84:87], v74 offset:34304
	ds_read_b128 v[92:95], v75 offset:33792
	v_add_f32_dpp v0, v0, v0 row_half_mirror row_mask:0xf bank_mask:0xf bound_ctrl:1
	ds_read_b128 v[88:91], v74 offset:34560
	v_pk_fma_f32 v[14:15], v[60:61], v[6:7], v[14:15]
	v_add_f32_dpp v0, v0, v0 row_mirror row_mask:0xf bank_mask:0xf bound_ctrl:1
	v_pk_fma_f32 v[58:59], v[8:9], v[0:1], v[12:13] op_sel_hi:[1,0,1]
	v_pk_fma_f32 v[60:61], v[10:11], v[0:1], v[14:15] op_sel_hi:[1,0,1]
	ds_read_b128 v[0:3], v74 offset:36864
	v_pk_mul_f32 v[20:21], v[58:59], v[20:21] op_sel_hi:[0,1]
	v_pk_fma_f32 v[20:21], v[58:59], v[22:23], v[20:21] op_sel:[1,0,0] op_sel_hi:[1,1,1]
	v_pk_fma_f32 v[20:21], v[60:61], v[36:37], v[20:21] op_sel_hi:[0,1,1]
	v_pk_fma_f32 v[20:21], v[60:61], v[38:39], v[20:21] op_sel:[1,0,0] op_sel_hi:[1,1,1]
	v_pk_fma_f32 v[32:33], v[58:59], v[24:25], v[32:33]
	v_pk_fma_f32 v[34:35], v[60:61], v[26:27], v[34:35]
	v_add_f32_dpp v20, v20, v20 quad_perm:[1,0,3,2] row_mask:0xf bank_mask:0xf bound_ctrl:1
	ds_read_b128 v[16:19], v74 offset:37120
	ds_read_b128 v[4:7], v74 offset:37376
	v_add_f32_dpp v20, v20, v20 quad_perm:[2,3,0,1] row_mask:0xf bank_mask:0xf bound_ctrl:1
	ds_read_b128 v[12:15], v75 offset:36864
	ds_read_b128 v[8:11], v74 offset:37632
	v_add_f32_dpp v20, v20, v20 row_half_mirror row_mask:0xf bank_mask:0xf bound_ctrl:1
	s_nop 1
	v_add_f32_dpp v20, v20, v20 row_mirror row_mask:0xf bank_mask:0xf bound_ctrl:1
	v_pk_fma_f32 v[58:59], v[28:29], v[20:21], v[32:33] op_sel_hi:[1,0,1]
	v_pk_fma_f32 v[60:61], v[30:31], v[20:21], v[34:35] op_sel_hi:[1,0,1]
	s_waitcnt lgkmcnt(5)
; #define LAS __attribute__((address_space(3)))
; #define RW_LDS_WAIT(X) asm volatile("s_waitcnt lgkmcnt(0)" : "+v"(nk##X), "+v"(dd##X), "+v"(bb##X), "+v"(kp##X), "+v"(rr##X), "+v"(vv##X) :: "memory")
; DI void rwkv_scan_phase(int wv, const Params& P, LAS unsigned char* lds) {
;     ...
;                 f32x2 yacc = (f32x2){0.f, 0.f};
;                 unsigned sbt = sba, vbt = vba; LAS float* ybt = yb;
;                 RW_LDS_LOAD(A, 0); RW_LDS_WAIT(A);
; #pragma unroll 1
;                 for (int tt = 0; tt < RW_T; tt += 16) { sbt = sba + (unsigned)tt * 1280u; vbt = vba + (unsigned)tt * 32u; ybt = yb + tt * 128;
;                     RW_LDS_LOAD(B, 1); RW_STEP(A, 0); RW_LDS_WAIT(B);
;                     RW_LDS_LOAD(A, 2); RW_STEP(B, 1); RW_LDS_WAIT(A);
;                     RW_LDS_LOAD(B, 3); RW_STEP(A, 2); RW_LDS_WAIT(B);
;                     RW_LDS_LOAD(A, 4); RW_STEP(B, 3); RW_LDS_WAIT(A);
;                     RW_LDS_LOAD(B, 5); RW_STEP(A, 4); RW_LDS_WAIT(B);
;                     RW_LDS_LOAD(A, 6); RW_STEP(B, 5); RW_LDS_WAIT(A);
;                     RW_LDS_LOAD(B, 7); RW_STEP(A, 6); RW_LDS_WAIT(B);
;                     RW_LDS_LOAD(A, 8); RW_STEP(B, 7); RW_LDS_WAIT(A);
;                     RW_LDS_LOAD(B, 9); RW_STEP(A, 8); RW_LDS_WAIT(B);
;                     RW_LDS_LOAD(A, 10); RW_STEP(B, 9); RW_LDS_WAIT(A);
;                     RW_LDS_LOAD(B, 11); RW_STEP(A, 10); RW_LDS_WAIT(B);
;                     RW_LDS_LOAD(A, 12); RW_STEP(B, 11); RW_LDS_WAIT(A);
;                     RW_LDS_LOAD(B, 13); RW_STEP(A, 12); RW_LDS_WAIT(B);
;                     RW_LDS_LOAD(A, 14); RW_STEP(B, 13); RW_LDS_WAIT(A);
;                     RW_LDS_LOAD(B, 15); RW_STEP(A, 14); RW_LDS_WAIT(B);
;                     RW_LDS_LOAD(A, 16); RW_STEP(B, 15); RW_LDS_WAIT(A);
;                 }
	v_pk_mul_f32 v[46:47], v[58:59], v[46:47] op_sel_hi:[0,1]
	v_pk_fma_f32 v[46:47], v[58:59], v[48:49], v[46:47] op_sel:[1,0,0] op_sel_hi:[1,1,1]
	v_pk_fma_f32 v[46:47], v[60:61], v[76:77], v[46:47] op_sel_hi:[0,1,1]
	v_pk_fma_f32 v[46:47], v[60:61], v[78:79], v[46:47] op_sel:[1,0,0] op_sel_hi:[1,1,1]
	ds_write2st64_b32 v72, v21, v47 offset0:16 offset1:18
	v_pk_fma_f32 v[68:69], v[58:59], v[50:51], v[68:69]
	v_add_f32_dpp v46, v46, v46 quad_perm:[1,0,3,2] row_mask:0xf bank_mask:0xf bound_ctrl:1
	ds_read_b128 v[20:23], v74 offset:39936
	ds_read_b128 v[36:39], v74 offset:40192
	v_add_f32_dpp v46, v46, v46 quad_perm:[2,3,0,1] row_mask:0xf bank_mask:0xf bound_ctrl:1
	ds_read_b128 v[24:27], v74 offset:40448
	ds_read_b128 v[32:35], v75 offset:39936
	v_add_f32_dpp v46, v46, v46 row_half_mirror row_mask:0xf bank_mask:0xf bound_ctrl:1
	ds_read_b128 v[28:31], v74 offset:40704
	v_pk_fma_f32 v[70:71], v[60:61], v[52:53], v[70:71]
	v_add_f32_dpp v46, v46, v46 row_mirror row_mask:0xf bank_mask:0xf bound_ctrl:1
	v_pk_fma_f32 v[58:59], v[54:55], v[46:47], v[68:69] op_sel_hi:[1,0,1]
	v_pk_fma_f32 v[60:61], v[56:57], v[46:47], v[70:71] op_sel_hi:[1,0,1]
	ds_read_b128 v[46:49], v74 offset:43008
	v_pk_mul_f32 v[80:81], v[58:59], v[80:81] op_sel_hi:[0,1]
	v_pk_fma_f32 v[80:81], v[58:59], v[82:83], v[80:81] op_sel:[1,0,0] op_sel_hi:[1,1,1]
	v_pk_fma_f32 v[80:81], v[60:61], v[96:97], v[80:81] op_sel_hi:[0,1,1]
	v_pk_fma_f32 v[80:81], v[60:61], v[98:99], v[80:81] op_sel:[1,0,0] op_sel_hi:[1,1,1]
	v_pk_fma_f32 v[92:93], v[58:59], v[84:85], v[92:93]
	v_pk_fma_f32 v[94:95], v[60:61], v[86:87], v[94:95]
	v_add_f32_dpp v80, v80, v80 quad_perm:[1,0,3,2] row_mask:0xf bank_mask:0xf bound_ctrl:1
	ds_read_b128 v[76:79], v74 offset:43264
	ds_read_b128 v[50:53], v74 offset:43520
	v_add_f32_dpp v80, v80, v80 quad_perm:[2,3,0,1] row_mask:0xf bank_mask:0xf bound_ctrl:1
	ds_read_b128 v[68:71], v75 offset:43008
	ds_read_b128 v[54:57], v74 offset:43776
	v_add_f32_dpp v80, v80, v80 row_half_mirror row_mask:0xf bank_mask:0xf bound_ctrl:1
	s_nop 1
	v_add_f32_dpp v80, v80, v80 row_mirror row_mask:0xf bank_mask:0xf bound_ctrl:1
	v_pk_fma_f32 v[58:59], v[88:89], v[80:81], v[92:93] op_sel_hi:[1,0,1]
	v_pk_fma_f32 v[60:61], v[90:91], v[80:81], v[94:95] op_sel_hi:[1,0,1]
	s_waitcnt lgkmcnt(5)
	v_pk_mul_f32 v[0:1], v[58:59], v[0:1] op_sel_hi:[0,1]
	v_pk_fma_f32 v[0:1], v[58:59], v[2:3], v[0:1] op_sel:[1,0,0] op_sel_hi:[1,1,1]
	v_pk_fma_f32 v[0:1], v[60:61], v[16:17], v[0:1] op_sel_hi:[0,1,1]
	v_pk_fma_f32 v[0:1], v[60:61], v[18:19], v[0:1] op_sel:[1,0,0] op_sel_hi:[1,1,1]
	ds_write2st64_b32 v72, v81, v1 offset0:20 offset1:22
	v_pk_fma_f32 v[12:13], v[58:59], v[4:5], v[12:13]
	v_add_f32_dpp v0, v0, v0 quad_perm:[1,0,3,2] row_mask:0xf bank_mask:0xf bound_ctrl:1
	ds_read_b128 v[80:83], v74 offset:46080
	ds_read_b128 v[96:99], v74 offset:46336
	v_add_f32_dpp v0, v0, v0 quad_perm:[2,3,0,1] row_mask:0xf bank_mask:0xf bound_ctrl:1
	ds_read_b128 v[84:87], v74 offset:46592
	ds_read_b128 v[92:95], v75 offset:46080
	v_add_f32_dpp v0, v0, v0 row_half_mirror row_mask:0xf bank_mask:0xf bound_ctrl:1
	ds_read_b128 v[88:91], v74 offset:46848
	v_pk_fma_f32 v[14:15], v[60:61], v[6:7], v[14:15]
	v_add_f32_dpp v0, v0, v0 row_mirror row_mask:0xf bank_mask:0xf bound_ctrl:1
	v_pk_fma_f32 v[58:59], v[8:9], v[0:1], v[12:13] op_sel_hi:[1,0,1]
	v_pk_fma_f32 v[60:61], v[10:11], v[0:1], v[14:15] op_sel_hi:[1,0,1]
	v_pk_mul_f32 v[20:21], v[58:59], v[20:21] op_sel_hi:[0,1]
	v_pk_fma_f32 v[20:21], v[58:59], v[22:23], v[20:21] op_sel:[1,0,0] op_sel_hi:[1,1,1]
	v_pk_fma_f32 v[20:21], v[60:61], v[36:37], v[20:21] op_sel_hi:[0,1,1]
	v_pk_fma_f32 v[20:21], v[60:61], v[38:39], v[20:21] op_sel:[1,0,0] op_sel_hi:[1,1,1]
	v_pk_fma_f32 v[32:33], v[58:59], v[24:25], v[32:33]
	v_pk_fma_f32 v[34:35], v[60:61], v[26:27], v[34:35]
	v_add_f32_dpp v20, v20, v20 quad_perm:[1,0,3,2] row_mask:0xf bank_mask:0xf bound_ctrl:1
	s_add_i32 s47, s47, 1
	s_add_i32 s42, s42, 0x2000
	v_add_f32_dpp v20, v20, v20 quad_perm:[2,3,0,1] row_mask:0xf bank_mask:0xf bound_ctrl:1
	s_cmp_eq_u32 s42, 0x6000
	s_cselect_b32 s42, 0, s42
	v_add_f32_dpp v20, v20, v20 row_half_mirror row_mask:0xf bank_mask:0xf bound_ctrl:1
	v_add_u32_e32 v67, s42, v62
	s_nop 0
	v_add_f32_dpp v20, v20, v20 row_mirror row_mask:0xf bank_mask:0xf bound_ctrl:1
	v_pk_fma_f32 v[58:59], v[28:29], v[20:21], v[32:33] op_sel_hi:[1,0,1]
	v_pk_fma_f32 v[60:61], v[30:31], v[20:21], v[34:35] op_sel_hi:[1,0,1]
	s_waitcnt lgkmcnt(0)
	s_barrier
; #define LAS __attribute__((address_space(3)))
; #define RW_LDS_WAIT(X) asm volatile("s_waitcnt lgkmcnt(0)" : "+v"(nk##X), "+v"(dd##X), "+v"(bb##X), "+v"(kp##X), "+v"(rr##X), "+v"(vv##X) :: "memory")
; DI void rwkv_scan_phase(int wv, const Params& P, LAS unsigned char* lds) {
;     ...
;                 f32x2 yacc = (f32x2){0.f, 0.f};
;                 unsigned sbt = sba, vbt = vba; LAS float* ybt = yb;
;                 RW_LDS_LOAD(A, 0); RW_LDS_WAIT(A);
; #pragma unroll 1
;                 for (int tt = 0; tt < RW_T; tt += 16) { sbt = sba + (unsigned)tt * 1280u; vbt = vba + (unsigned)tt * 32u; ybt = yb + tt * 128;
;                     RW_LDS_LOAD(B, 1); RW_STEP(A, 0); RW_LDS_WAIT(B);
;                     RW_LDS_LOAD(A, 2); RW_STEP(B, 1); RW_LDS_WAIT(A);
;                     RW_LDS_LOAD(B, 3); RW_STEP(A, 2); RW_LDS_WAIT(B);
;                     RW_LDS_LOAD(A, 4); RW_STEP(B, 3); RW_LDS_WAIT(A);
;                     RW_LDS_LOAD(B, 5); RW_STEP(A, 4); RW_LDS_WAIT(B);
;                     RW_LDS_LOAD(A, 6); RW_STEP(B, 5); RW_LDS_WAIT(A);
;                     RW_LDS_LOAD(B, 7); RW_STEP(A, 6); RW_LDS_WAIT(B);
;                     RW_LDS_LOAD(A, 8); RW_STEP(B, 7); RW_LDS_WAIT(A);
;                     RW_LDS_LOAD(B, 9); RW_STEP(A, 8); RW_LDS_WAIT(B);
;                     RW_LDS_LOAD(A, 10); RW_STEP(B, 9); RW_LDS_WAIT(A);
;                     RW_LDS_LOAD(B, 11); RW_STEP(A, 10); RW_LDS_WAIT(B);
;                     RW_LDS_LOAD(A, 12); RW_STEP(B, 11); RW_LDS_WAIT(A);
;                     RW_LDS_LOAD(B, 13); RW_STEP(A, 12); RW_LDS_WAIT(B);
;                     RW_LDS_LOAD(A, 14); RW_STEP(B, 13); RW_LDS_WAIT(A);
;                     RW_LDS_LOAD(B, 15); RW_STEP(A, 14); RW_LDS_WAIT(B);
;                     RW_LDS_LOAD(A, 16); RW_STEP(B, 15); RW_LDS_WAIT(A);
;                 }
;                 yb[(RW_T - 1) * 128] = yacc[0] + yacc[1];
	v_xor_b32_e32 v74, 0xc000, v74
	v_xor_b32_e32 v75, 0xc000, v75
	v_pk_mul_f32 v[46:47], v[58:59], v[46:47] op_sel_hi:[0,1]
	v_pk_fma_f32 v[46:47], v[58:59], v[48:49], v[46:47] op_sel:[1,0,0] op_sel_hi:[1,1,1]
	v_pk_fma_f32 v[46:47], v[60:61], v[76:77], v[46:47] op_sel_hi:[0,1,1]
	v_pk_fma_f32 v[46:47], v[60:61], v[78:79], v[46:47] op_sel:[1,0,0] op_sel_hi:[1,1,1]
	ds_write2st64_b32 v72, v21, v47 offset0:24 offset1:26
	v_pk_fma_f32 v[68:69], v[58:59], v[50:51], v[68:69]
	v_add_f32_dpp v46, v46, v46 quad_perm:[1,0,3,2] row_mask:0xf bank_mask:0xf bound_ctrl:1
	ds_read_b128 v[0:3], v74
	ds_read_b128 v[16:19], v74 offset:256
	v_add_f32_dpp v46, v46, v46 quad_perm:[2,3,0,1] row_mask:0xf bank_mask:0xf bound_ctrl:1
	ds_read_b128 v[4:7], v74 offset:512
	ds_read_b128 v[12:15], v75
	v_add_f32_dpp v46, v46, v46 row_half_mirror row_mask:0xf bank_mask:0xf bound_ctrl:1
	ds_read_b128 v[8:11], v74 offset:768
	v_pk_fma_f32 v[70:71], v[60:61], v[52:53], v[70:71]
	v_add_f32_dpp v46, v46, v46 row_mirror row_mask:0xf bank_mask:0xf bound_ctrl:1
	ds_read_b128 v[20:23], v74 offset:3072
	ds_read_b128 v[36:39], v74 offset:3328
	ds_read_b128 v[24:27], v74 offset:3584
	ds_read_b128 v[32:35], v75 offset:3072
	ds_read_b128 v[28:31], v74 offset:3840
	v_pk_fma_f32 v[58:59], v[54:55], v[46:47], v[68:69] op_sel_hi:[1,0,1]
	v_pk_fma_f32 v[60:61], v[56:57], v[46:47], v[70:71] op_sel_hi:[1,0,1]
	v_pk_mul_f32 v[80:81], v[58:59], v[80:81] op_sel_hi:[0,1]
	v_pk_fma_f32 v[80:81], v[58:59], v[82:83], v[80:81] op_sel:[1,0,0] op_sel_hi:[1,1,1]
	v_pk_fma_f32 v[80:81], v[60:61], v[96:97], v[80:81] op_sel_hi:[0,1,1]
	v_pk_fma_f32 v[80:81], v[60:61], v[98:99], v[80:81] op_sel:[1,0,0] op_sel_hi:[1,1,1]
	v_pk_fma_f32 v[92:93], v[58:59], v[84:85], v[92:93]
	v_pk_fma_f32 v[94:95], v[60:61], v[86:87], v[94:95]
	v_add_f32_dpp v80, v80, v80 quad_perm:[1,0,3,2] row_mask:0xf bank_mask:0xf bound_ctrl:1
	ds_read_b128 v[46:49], v74 offset:6144
	ds_read_b128 v[76:79], v74 offset:6400
	v_add_f32_dpp v80, v80, v80 quad_perm:[2,3,0,1] row_mask:0xf bank_mask:0xf bound_ctrl:1
	ds_read_b128 v[50:53], v74 offset:6656
	ds_read_b128 v[68:71], v75 offset:6144
	v_add_f32_dpp v80, v80, v80 row_half_mirror row_mask:0xf bank_mask:0xf bound_ctrl:1
	ds_read_b128 v[54:57], v74 offset:6912
	s_cmpk_eq_i32 s47, 0x200
	v_add_f32_dpp v80, v80, v80 row_mirror row_mask:0xf bank_mask:0xf bound_ctrl:1
	v_pk_fma_f32 v[58:59], v[88:89], v[80:81], v[92:93] op_sel_hi:[1,0,1]
	v_pk_fma_f32 v[60:61], v[90:91], v[80:81], v[94:95] op_sel_hi:[1,0,1]
	s_cbranch_scc0 .Lscan_chunk
	v_add_u32_e32 v40, 0x1e100, v45
	ds_read_b128 v[84:87], v40
	s_waitcnt lgkmcnt(0)
	v_pk_mul_f32 v[64:65], v[84:85], v[58:59]
	v_pk_fma_f32 v[64:65], v[86:87], v[60:61], v[64:65]
	s_nop 0
	v_add_f32_e32 v64, v64, v65
	ds_write2st64_b32 v72, v81, v64 offset0:28 offset1:30
	s_waitcnt lgkmcnt(0)
	s_barrier
